# v031 + P0: h0 and transposed-weight stores made write-through (full-line stores), nothing left dirty in L2 at the first grid barrier
# speedup vs baseline: 1.0242x; 1.0033x over previous
; __device__ __forceinline__ unsigned cvt_pk_bf16(float lo, float hi) { unsigned r; asm volatile("v_cvt_pk_bf16_f32 %0, %1, %2" : "=v"(r) : "v"(lo), "v"(hi)); return r; }
; __device__ __forceinline__ void p0_prologue(const Params& p, LAS unsigned char* lds, int G) {
;     ...
;     for (int m = gw; m < MT; m += NGW) {
;         const float* xrow = (m < MP) ? p.xp + (size_t)m * DM : p.xs + (size_t)(m - MP) * DM;
;         f32x4 v[8]; float s = 0.f;
; #pragma unroll
;         for (int j = 0; j < 8; ++j) { v[j] = __builtin_nontemporal_load((const f32x4*)(xrow + 4 * lane + 256 * j)); s += (v[j][0] * v[j][0] + v[j][1] * v[j][1]) + (v[j][2] * v[j][2] + v[j][3] * v[j][3]); }
;         const float rinv = __builtin_amdgcn_rsqf(wave_sum(s) * (1.0f / DM) + 1e-6f);
; #pragma unroll
;         for (int j = 0; j < 8; ++j) { const f32x4 gg = *(const f32x4*)(p.norm_g + 4 * lane + 256 * j);
;             u32x2 w; w.x = cvt_pk_bf16(v[j][0] * rinv * gg[0], v[j][1] * rinv * gg[1]); w.y = cvt_pk_bf16(v[j][2] * rinv * gg[2], v[j][3] * rinv * gg[3]);
;             *(u32x2*)(h0 + (size_t)m * DM + 4 * lane + 256 * j) = w; }
;     }
.LBB0_7:
	s_or_b64 exec, exec, s[8:9]
	v_lshl_add_u64 v[2:3], v[2:3], 0, v[30:31]
	global_load_dwordx4 v[44:47], v[2:3], off nt
	global_load_dwordx4 v[48:51], v[2:3], off offset:1024 nt
	global_load_dwordx4 v[52:55], v[2:3], off offset:2048 nt
	global_load_dwordx4 v[56:59], v[2:3], off offset:3072 nt
	v_add_co_u32_e32 v2, vcc, s11, v2
	v_lshlrev_b64 v[34:35], 12, v[34:35]
	s_nop 0
	v_addc_co_u32_e32 v3, vcc, 0, v3, vcc
	global_load_dwordx4 v[60:63], v[2:3], off nt
	global_load_dwordx4 v[6:9], v[2:3], off offset:1024 nt
	global_load_dwordx4 v[64:67], v[2:3], off offset:2048 nt
	s_nop 0
	global_load_dwordx4 v[2:5], v[2:3], off offset:3072 nt
	s_nop 0
	v_lshl_add_u64 v[34:35], v[16:17], 0, v[34:35]
	v_lshl_add_u64 v[32:33], v[32:33], 0, s[96:97]
	v_cmp_lt_i32_e32 vcc, s12, v32
	s_or_b64 s[6:7], vcc, s[6:7]
	v_lshl_add_u64 v[28:29], v[28:29], 0, s[4:5]
	s_waitcnt vmcnt(7)
	v_mul_f32_e32 v11, v45, v45
	v_mul_f32_e32 v14, v47, v47
	s_waitcnt vmcnt(6)
	v_mul_f32_e32 v72, v49, v49
	v_mul_f32_e32 v73, v51, v51
	s_waitcnt vmcnt(5)
	v_mul_f32_e32 v74, v53, v53
	v_mul_f32_e32 v75, v55, v55
	v_fmac_f32_e32 v11, v44, v44
	v_fmac_f32_e32 v14, v46, v46
	v_fmac_f32_e32 v72, v48, v48
	v_fmac_f32_e32 v73, v50, v50
	s_waitcnt vmcnt(4)
	v_mul_f32_e32 v76, v57, v57
	v_mul_f32_e32 v77, v59, v59
	v_fmac_f32_e32 v74, v52, v52
	v_fmac_f32_e32 v75, v54, v54
	v_add_f32_e32 v11, v11, v14
	v_add_f32_e32 v14, v72, v73
	v_fmac_f32_e32 v76, v56, v56
	v_fmac_f32_e32 v77, v58, v58
	s_waitcnt vmcnt(3)
	v_mul_f32_e32 v78, v61, v61
	v_mul_f32_e32 v79, v63, v63
	v_add_f32_e32 v72, v74, v75
	v_add_f32_e32 v11, v11, v14
	s_waitcnt vmcnt(2)
	v_mul_f32_e32 v80, v7, v7
	v_mul_f32_e32 v81, v9, v9
	v_add_f32_e32 v73, v76, v77
	v_fmac_f32_e32 v78, v60, v60
	v_fmac_f32_e32 v79, v62, v62
	v_add_f32_e32 v11, v11, v72
	s_waitcnt vmcnt(1)
	v_mul_f32_e32 v82, v65, v65
	v_mul_f32_e32 v83, v67, v67
	v_fmac_f32_e32 v80, v6, v6
	v_fmac_f32_e32 v81, v8, v8
	v_add_f32_e32 v14, v78, v79
	v_add_f32_e32 v11, v11, v73
	s_waitcnt vmcnt(0)
	v_mul_f32_e32 v84, v3, v3
	v_mul_f32_e32 v85, v5, v5
	v_fmac_f32_e32 v82, v64, v64
	v_fmac_f32_e32 v83, v66, v66
	v_add_f32_e32 v74, v80, v81
	v_add_f32_e32 v11, v11, v14
	v_fmac_f32_e32 v84, v2, v2
	v_fmac_f32_e32 v85, v4, v4
	v_add_f32_e32 v75, v82, v83
	v_add_f32_e32 v11, v11, v74
	v_add_f32_e32 v76, v84, v85
	v_add_f32_e32 v11, v11, v75
	v_add_f32_e32 v11, v11, v76
	ds_bpermute_b32 v14, v38, v11
	s_waitcnt lgkmcnt(0)
	v_add_f32_e32 v11, v11, v14
	ds_bpermute_b32 v14, v39, v11
	s_waitcnt lgkmcnt(0)
	v_add_f32_e32 v11, v11, v14
	ds_bpermute_b32 v14, v40, v11
	s_waitcnt lgkmcnt(0)
	v_add_f32_e32 v11, v11, v14
	ds_bpermute_b32 v14, v41, v11
	s_waitcnt lgkmcnt(0)
	v_add_f32_e32 v11, v11, v14
	ds_bpermute_b32 v14, v42, v11
	s_waitcnt lgkmcnt(0)
	v_add_f32_e32 v11, v11, v14
	ds_bpermute_b32 v14, v43, v11
	s_waitcnt lgkmcnt(0)
	v_add_f32_e32 v11, v11, v14
	v_fmamk_f32 v11, v11, 0x3a000000, v13
	v_rsq_f32_e32 v11, v11
	s_nop 0
	v_mul_f32_e32 v14, v44, v11
	v_mul_f32_e32 v44, v45, v11
	v_mul_f32_e32 v45, v46, v11
	v_mul_f32_e32 v46, v47, v11
	v_mov_b32_e32 v68, v120
	v_mov_b32_e32 v69, v121
	v_mov_b32_e32 v70, v122
	v_mov_b32_e32 v71, v123
	v_mul_f32_e32 v44, v69, v44
	v_mul_f32_e32 v45, v70, v45
	v_mul_f32_e32 v14, v68, v14
	v_mul_f32_e32 v46, v71, v46
	v_cvt_pk_bf16_f32 v44, v14, v44
	v_cvt_pk_bf16_f32 v45, v45, v46
	global_store_dwordx2 v[34:35], v[44:45], off sc1
	v_mov_b32_e32 v44, v124
	v_mov_b32_e32 v45, v125
	v_mov_b32_e32 v46, v126
	v_mov_b32_e32 v47, v127
	v_mul_f32_e32 v14, v48, v11
	v_mul_f32_e32 v48, v49, v11
	v_mul_f32_e32 v49, v50, v11
	v_mul_f32_e32 v50, v51, v11
	v_mul_f32_e32 v6, v6, v11
	v_mul_f32_e32 v7, v7, v11
	v_mul_f32_e32 v8, v8, v11
	v_mul_f32_e32 v9, v9, v11
	v_mul_f32_e32 v2, v2, v11
	v_mul_f32_e32 v3, v3, v11
	v_mul_f32_e32 v4, v4, v11
	v_mul_f32_e32 v5, v5, v11
	v_mul_f32_e32 v14, v44, v14
	v_mul_f32_e32 v44, v45, v48
	v_mul_f32_e32 v45, v46, v49
	v_mul_f32_e32 v46, v47, v50
	v_cvt_pk_bf16_f32 v44, v14, v44
	v_cvt_pk_bf16_f32 v45, v45, v46
	global_store_dwordx2 v[34:35], v[44:45], off offset:512 sc1
	v_mov_b32_e32 v44, v128
	v_mov_b32_e32 v45, v129
	v_mov_b32_e32 v46, v130
	v_mov_b32_e32 v47, v131
	v_mul_f32_e32 v14, v52, v11
	v_mul_f32_e32 v48, v53, v11
	v_mul_f32_e32 v49, v54, v11
	v_mul_f32_e32 v50, v55, v11
	v_mul_f32_e32 v14, v14, v44
	v_mul_f32_e32 v44, v48, v45
	v_mul_f32_e32 v45, v49, v46
	v_mul_f32_e32 v46, v50, v47
	v_cvt_pk_bf16_f32 v44, v14, v44
	v_cvt_pk_bf16_f32 v45, v45, v46
	global_store_dwordx2 v[34:35], v[44:45], off offset:1024 sc1
	v_mov_b32_e32 v44, v132
	v_mov_b32_e32 v45, v133
	v_mov_b32_e32 v46, v134
	v_mov_b32_e32 v47, v135
	v_mul_f32_e32 v14, v56, v11
	v_mul_f32_e32 v48, v57, v11
	v_mul_f32_e32 v49, v58, v11
	v_mul_f32_e32 v50, v59, v11
	v_mul_f32_e32 v14, v14, v44
	v_mul_f32_e32 v44, v48, v45
	v_mul_f32_e32 v45, v49, v46
	v_mul_f32_e32 v46, v50, v47
	v_cvt_pk_bf16_f32 v44, v14, v44
	v_cvt_pk_bf16_f32 v45, v45, v46
	global_store_dwordx2 v[34:35], v[44:45], off offset:1536 sc1
	v_mov_b32_e32 v44, v136
	v_mov_b32_e32 v45, v137
	v_mov_b32_e32 v46, v138
	v_mov_b32_e32 v47, v139
	v_mul_f32_e32 v14, v60, v11
	v_mul_f32_e32 v48, v61, v11
	v_mul_f32_e32 v49, v62, v11
	v_mul_f32_e32 v50, v63, v11
	v_mul_f32_e32 v14, v14, v44
	v_mul_f32_e32 v44, v48, v45
	v_mul_f32_e32 v45, v49, v46
	v_mul_f32_e32 v46, v50, v47
	v_cvt_pk_bf16_f32 v44, v14, v44
	v_cvt_pk_bf16_f32 v45, v45, v46
	global_store_dwordx2 v[34:35], v[44:45], off offset:2048 sc1
	v_mov_b32_e32 v44, v140
	v_mov_b32_e32 v45, v141
	v_mov_b32_e32 v46, v142
	v_mov_b32_e32 v47, v143
	v_mul_f32_e32 v14, v64, v11
	v_mul_f32_e32 v6, v6, v44
	v_mul_f32_e32 v7, v7, v45
	v_mul_f32_e32 v8, v8, v46
	v_mul_f32_e32 v9, v9, v47
	v_cvt_pk_bf16_f32 v6, v6, v7
	v_cvt_pk_bf16_f32 v7, v8, v9
	global_store_dwordx2 v[34:35], v[6:7], off offset:2560 sc1
	v_mov_b32_e32 v6, v144
	v_mov_b32_e32 v7, v145
	v_mov_b32_e32 v8, v146
	v_mov_b32_e32 v9, v147
	v_mul_f32_e32 v44, v65, v11
	v_mul_f32_e32 v45, v66, v11
	v_mul_f32_e32 v46, v67, v11
	v_mul_f32_e32 v6, v14, v6
	v_mul_f32_e32 v7, v44, v7
	v_mul_f32_e32 v8, v45, v8
	v_mul_f32_e32 v9, v46, v9
	v_cvt_pk_bf16_f32 v6, v6, v7
	v_cvt_pk_bf16_f32 v7, v8, v9
	global_store_dwordx2 v[34:35], v[6:7], off offset:3072 sc1
	v_mov_b32_e32 v6, v148
	v_mov_b32_e32 v7, v149
	v_mov_b32_e32 v8, v150
	v_mov_b32_e32 v9, v151
	v_mul_f32_e32 v2, v2, v6
	v_mul_f32_e32 v3, v3, v7
	v_mul_f32_e32 v4, v4, v8
	v_mul_f32_e32 v5, v5, v9
	v_cvt_pk_bf16_f32 v2, v2, v3
	v_cvt_pk_bf16_f32 v3, v4, v5
	global_store_dwordx2 v[34:35], v[2:3], off offset:3584 sc1
	s_andn2_b64 exec, exec, s[6:7]
	s_cbranch_execz .LBB0_10

; __device__ __forceinline__ void p0_transpose_item(const float* W, int K, int N, bf16_t* WT, const float* gk, LAS float* scr, int item, int lane, bool w1map) {
;     const int nblk = N / 32, kb = item / nblk, nb = item % nblk, k0 = 64 * kb, n0 = 32 * nb;
;     int nd0 = n0;
;     if (w1map) { if (n0 < GW) nd0 = (n0 >> 7) * 256 + (n0 & 127); else if (n0 < 2 * GW) nd0 = 2 * GW + (n0 - GW); else { const int c = n0 - 2 * GW; nd0 = (c >> 7) * 256 + 128 + (c & 127); } }
;     float wv[32];
; #pragma unroll
;     for (int i = 0; i < 32; ++i) wv[i] = __builtin_nontemporal_load(W + (size_t)(k0 + 2 * i + (lane >> 5)) * N + n0 + (lane & 31));
.LBB0_12:
	s_or_b64 exec, exec, s[10:11]
	v_lshlrev_b32_e32 v42, 6, v23
	v_or_b32_e32 v43, v42, v1
	v_ashrrev_i32_e32 v23, 31, v22
	v_lshl_add_u64 v[22:23], v[22:23], 2, v[20:21]
	v_or_b32_e32 v40, 2, v43
	v_or_b32_e32 v44, 4, v43
	v_or_b32_e32 v46, 6, v43
	v_or_b32_e32 v48, 8, v43
	v_or_b32_e32 v50, 10, v43
	v_or_b32_e32 v52, 12, v43
	v_or_b32_e32 v54, 14, v43
	v_mad_i64_i32 v[38:39], s[10:11], v43, s25, v[22:23]
	v_mad_i64_i32 v[40:41], s[10:11], v40, s25, v[22:23]
	v_mad_i64_i32 v[44:45], s[10:11], v44, s25, v[22:23]
	v_mad_i64_i32 v[46:47], s[10:11], v46, s25, v[22:23]
	v_mad_i64_i32 v[48:49], s[10:11], v48, s25, v[22:23]
	v_mad_i64_i32 v[50:51], s[10:11], v50, s25, v[22:23]
	v_mad_i64_i32 v[52:53], s[10:11], v52, s25, v[22:23]
	v_mad_i64_i32 v[54:55], s[10:11], v54, s25, v[22:23]
	global_load_dword v56, v[38:39], off nt
	global_load_dword v57, v[40:41], off nt
	global_load_dword v58, v[44:45], off nt
	global_load_dword v59, v[46:47], off nt
	global_load_dword v60, v[48:49], off nt
	global_load_dword v61, v[50:51], off nt
	global_load_dword v62, v[52:53], off nt
	global_load_dword v63, v[54:55], off nt
	v_or_b32_e32 v38, 16, v43
	v_or_b32_e32 v40, 18, v43
	v_or_b32_e32 v44, 20, v43
	v_or_b32_e32 v46, 22, v43
	v_or_b32_e32 v48, 24, v43
	v_or_b32_e32 v50, 26, v43
	v_or_b32_e32 v52, 28, v43
	v_or_b32_e32 v54, 30, v43
	v_mad_i64_i32 v[38:39], s[10:11], v38, s25, v[22:23]
	v_mad_i64_i32 v[40:41], s[10:11], v40, s25, v[22:23]
	v_mad_i64_i32 v[44:45], s[10:11], v44, s25, v[22:23]
	v_mad_i64_i32 v[46:47], s[10:11], v46, s25, v[22:23]
	v_mad_i64_i32 v[48:49], s[10:11], v48, s25, v[22:23]
	v_mad_i64_i32 v[50:51], s[10:11], v50, s25, v[22:23]
	v_mad_i64_i32 v[52:53], s[10:11], v52, s25, v[22:23]
	v_mad_i64_i32 v[54:55], s[10:11], v54, s25, v[22:23]
	global_load_dword v64, v[38:39], off nt
	global_load_dword v65, v[40:41], off nt
	global_load_dword v66, v[44:45], off nt
	global_load_dword v67, v[46:47], off nt
	global_load_dword v68, v[48:49], off nt
	global_load_dword v69, v[50:51], off nt
	global_load_dword v70, v[52:53], off nt
	global_load_dword v71, v[54:55], off nt
	v_or_b32_e32 v38, 32, v43
	v_or_b32_e32 v40, 34, v43
	v_or_b32_e32 v44, 36, v43
	v_or_b32_e32 v46, 38, v43
	v_or_b32_e32 v48, 40, v43
	v_or_b32_e32 v50, 42, v43
	v_or_b32_e32 v52, 44, v43
	v_or_b32_e32 v54, 46, v43
	v_mad_i64_i32 v[38:39], s[10:11], v38, s25, v[22:23]
	v_mad_i64_i32 v[40:41], s[10:11], v40, s25, v[22:23]
	v_mad_i64_i32 v[44:45], s[10:11], v44, s25, v[22:23]
	v_mad_i64_i32 v[46:47], s[10:11], v46, s25, v[22:23]
	v_mad_i64_i32 v[48:49], s[10:11], v48, s25, v[22:23]
	v_mad_i64_i32 v[50:51], s[10:11], v50, s25, v[22:23]
	v_mad_i64_i32 v[52:53], s[10:11], v52, s25, v[22:23]
	v_mad_i64_i32 v[54:55], s[10:11], v54, s25, v[22:23]
	global_load_dword v72, v[38:39], off nt
	global_load_dword v73, v[40:41], off nt
	global_load_dword v74, v[44:45], off nt
	global_load_dword v75, v[46:47], off nt
	global_load_dword v76, v[48:49], off nt
	global_load_dword v77, v[50:51], off nt
	global_load_dword v78, v[52:53], off nt
	s_nop 0
	global_load_dword v54, v[54:55], off nt
	v_or_b32_e32 v38, 48, v43
	v_or_b32_e32 v40, 50, v43
	v_or_b32_e32 v44, 52, v43
	v_or_b32_e32 v46, 54, v43
	v_or_b32_e32 v48, 56, v43
	v_or_b32_e32 v50, 58, v43
	v_or_b32_e32 v52, 60, v43
	v_or_b32_e32 v43, 62, v43
	v_mad_i64_i32 v[38:39], s[10:11], v38, s25, v[22:23]
	v_mad_i64_i32 v[40:41], s[10:11], v40, s25, v[22:23]
	v_mad_i64_i32 v[44:45], s[10:11], v44, s25, v[22:23]
	v_mad_i64_i32 v[46:47], s[10:11], v46, s25, v[22:23]
	v_mad_i64_i32 v[48:49], s[10:11], v48, s25, v[22:23]
	v_mad_i64_i32 v[50:51], s[10:11], v50, s25, v[22:23]
	v_mad_i64_i32 v[52:53], s[10:11], v52, s25, v[22:23]
	v_mad_i64_i32 v[22:23], s[10:11], v43, s25, v[22:23]
	global_load_dword v38, v[38:39], off nt
	s_nop 0
	global_load_dword v39, v[40:41], off nt
	s_nop 0
	global_load_dword v40, v[44:45], off nt
	global_load_dword v41, v[46:47], off nt
	global_load_dword v43, v[48:49], off nt
	s_nop 0
	global_load_dword v44, v[50:51], off nt
	global_load_dword v45, v[52:53], off nt
	s_nop 0
	global_load_dword v22, v[22:23], off nt
	s_waitcnt vmcnt(30)
; #define LAS __attribute__((address_space(3)))
; __device__ __forceinline__ unsigned cvt_pk_bf16(float lo, float hi) { unsigned r; asm volatile("v_cvt_pk_bf16_f32 %0, %1, %2" : "=v"(r) : "v"(lo), "v"(hi)); return r; }
; __device__ __forceinline__ void p0_transpose_item(const float* W, int K, int N, bf16_t* WT, const float* gk, LAS float* scr, int item, int lane, bool w1map) {
;     ...
;     for (int i = 0; i < 32; ++i) scr[(2 * i + (lane >> 5)) * 33 + (lane & 31)] = wv[i];
;     asm volatile("s_waitcnt lgkmcnt(0)" ::: "memory");
;     const int c = lane & 7;
; #pragma unroll
;     for (int j = 0; j < 4; ++j) { const int n = (lane >> 3) + 8 * j; const LAS float* s = scr + (8 * c) * 33 + n;
;         u32x4 o; o.x = cvt_pk_bf16(s[0 * 33], s[1 * 33]); o.y = cvt_pk_bf16(s[2 * 33], s[3 * 33]); o.z = cvt_pk_bf16(s[4 * 33], s[5 * 33]); o.w = cvt_pk_bf16(s[6 * 33], s[7 * 33]);
;         *(u32x4*)(WT + (size_t)(nd0 + n) * K + k0 + 8 * c) = o; }
;     asm volatile("s_waitcnt lgkmcnt(0)" ::: "memory");
	ds_write2_b32 v11, v56, v57 offset1:66
	s_waitcnt vmcnt(28)
	ds_write2_b32 v11, v58, v59 offset0:132 offset1:198
	s_waitcnt vmcnt(26)
	ds_write2_b32 v31, v60, v61 offset0:8 offset1:74
	s_waitcnt vmcnt(24)
	ds_write2_b32 v31, v62, v63 offset0:140 offset1:206
	s_waitcnt vmcnt(22)
	ds_write2_b32 v32, v64, v65 offset0:16 offset1:82
	s_waitcnt vmcnt(20)
	ds_write2_b32 v32, v66, v67 offset0:148 offset1:214
	s_waitcnt vmcnt(18)
	ds_write2_b32 v33, v68, v69 offset0:24 offset1:90
	s_waitcnt vmcnt(16)
	ds_write2_b32 v33, v70, v71 offset0:156 offset1:222
	s_waitcnt vmcnt(14)
	ds_write2_b32 v34, v72, v73 offset0:32 offset1:98
	s_waitcnt vmcnt(12)
	ds_write2_b32 v34, v74, v75 offset0:164 offset1:230
	s_waitcnt vmcnt(10)
	ds_write2_b32 v35, v76, v77 offset0:40 offset1:106
	s_waitcnt vmcnt(8)
	ds_write2_b32 v35, v78, v54 offset0:172 offset1:238
	s_waitcnt vmcnt(6)
	ds_write2_b32 v36, v38, v39 offset0:48 offset1:114
	s_waitcnt vmcnt(4)
	ds_write2_b32 v36, v40, v41 offset0:180 offset1:246
	s_waitcnt vmcnt(2)
	ds_write2_b32 v37, v43, v44 offset0:56 offset1:122
	s_waitcnt vmcnt(0)
	ds_write2_b32 v37, v45, v22 offset0:188 offset1:254
	s_waitcnt lgkmcnt(0)
	ds_read2_b32 v[22:23], v25 offset1:33
	s_waitcnt lgkmcnt(0)
	v_cvt_pk_bf16_f32 v38, v22, v23
	ds_read2_b32 v[22:23], v25 offset0:66 offset1:99
	s_waitcnt lgkmcnt(0)
	v_cvt_pk_bf16_f32 v39, v22, v23
	ds_read2_b32 v[22:23], v25 offset0:132 offset1:165
	s_waitcnt lgkmcnt(0)
	v_cvt_pk_bf16_f32 v40, v22, v23
	ds_read2_b32 v[22:23], v25 offset0:198 offset1:231
	s_waitcnt lgkmcnt(0)
	v_cvt_pk_bf16_f32 v41, v22, v23
	v_add_u32_e32 v22, v2, v24
	v_ashrrev_i32_e32 v43, 31, v42
	v_ashrrev_i32_e32 v23, 31, v22
	v_lshl_add_u64 v[42:43], v[42:43], 1, v[12:13]
	v_lshlrev_b64 v[22:23], 12, v[22:23]
	v_lshl_add_u64 v[22:23], v[42:43], 0, v[22:23]
	ds_read2_b32 v[44:45], v25 offset0:8 offset1:41
	global_store_dwordx4 v[22:23], v[38:41], off sc1
	s_waitcnt lgkmcnt(0)
	s_nop 0
	v_cvt_pk_bf16_f32 v38, v44, v45
	ds_read2_b32 v[22:23], v25 offset0:74 offset1:107
	s_waitcnt lgkmcnt(0)
	v_cvt_pk_bf16_f32 v39, v22, v23
	ds_read2_b32 v[22:23], v25 offset0:140 offset1:173
	s_waitcnt lgkmcnt(0)
	v_cvt_pk_bf16_f32 v40, v22, v23
	ds_read2_b32 v[22:23], v25 offset0:206 offset1:239
	s_waitcnt lgkmcnt(0)
	v_cvt_pk_bf16_f32 v41, v22, v23
	v_add_u32_e32 v22, v2, v26
	v_ashrrev_i32_e32 v23, 31, v22
	v_lshlrev_b64 v[22:23], 12, v[22:23]
	v_lshl_add_u64 v[22:23], v[42:43], 0, v[22:23]
	ds_read2_b32 v[44:45], v25 offset0:16 offset1:49
	global_store_dwordx4 v[22:23], v[38:41], off sc1
	s_waitcnt lgkmcnt(0)
	s_nop 0
	v_cvt_pk_bf16_f32 v38, v44, v45
	ds_read2_b32 v[22:23], v25 offset0:82 offset1:115
	s_waitcnt lgkmcnt(0)
	v_cvt_pk_bf16_f32 v39, v22, v23
	ds_read2_b32 v[22:23], v25 offset0:148 offset1:181
	s_waitcnt lgkmcnt(0)
	v_cvt_pk_bf16_f32 v40, v22, v23
	ds_read2_b32 v[22:23], v25 offset0:214 offset1:247
	s_waitcnt lgkmcnt(0)
	v_cvt_pk_bf16_f32 v41, v22, v23
	v_add_u32_e32 v22, v2, v27
	v_ashrrev_i32_e32 v23, 31, v22
	v_lshlrev_b64 v[22:23], 12, v[22:23]
	v_lshl_add_u64 v[22:23], v[42:43], 0, v[22:23]
	ds_read2_b32 v[44:45], v25 offset0:24 offset1:57
	global_store_dwordx4 v[22:23], v[38:41], off sc1
	s_waitcnt lgkmcnt(0)
	s_nop 0
	v_cvt_pk_bf16_f32 v38, v44, v45
	ds_read2_b32 v[22:23], v25 offset0:90 offset1:123
	s_waitcnt lgkmcnt(0)
	v_cvt_pk_bf16_f32 v39, v22, v23
	ds_read2_b32 v[22:23], v25 offset0:156 offset1:189
	s_waitcnt lgkmcnt(0)
	v_cvt_pk_bf16_f32 v40, v22, v23
	ds_read2_b32 v[22:23], v25 offset0:222 offset1:255
	s_waitcnt lgkmcnt(0)
	v_cvt_pk_bf16_f32 v41, v22, v23
	v_add_u32_e32 v22, v2, v28
	v_ashrrev_i32_e32 v23, 31, v22
	v_lshlrev_b64 v[22:23], 12, v[22:23]
	v_lshl_add_u64 v[22:23], v[42:43], 0, v[22:23]
	global_store_dwordx4 v[22:23], v[38:41], off sc1
	s_waitcnt lgkmcnt(0)

; __device__ __forceinline__ void p0_transpose_item(const float* W, int K, int N, bf16_t* WT, const float* gk, LAS float* scr, int item, int lane, bool w1map) {
;     ...
;     float wv[32];
; #pragma unroll
;     for (int i = 0; i < 32; ++i) wv[i] = __builtin_nontemporal_load(W + (size_t)(k0 + 2 * i + (lane >> 5)) * N + n0 + (lane & 31));
;     if (gk) {
; #pragma unroll
;         for (int i = 0; i < 32; ++i) wv[i] *= gk[k0 + 2 * i + (lane >> 5)];
;     }
; #pragma unroll
;     for (int i = 0; i < 32; ++i) scr[(2 * i + (lane >> 5)) * 33 + (lane & 31)] = wv[i];
; __device__ __forceinline__ void p0_prologue(const Params& p, LAS unsigned char* lds, int G) {
;     ...
;         if (r < I1) { p0_transpose_item(p.w1, DM, N1, W1T, nullptr, scr, r, lane, true); continue; } r -= I1;
;         if (r < I2) { p0_transpose_item(p.w2, GW, DM, W2T, nullptr, scr, r, lane, false); continue; } r -= I2;
;         if (r < I3) { p0_transpose_item(p.w3, DM, N3, W3T, p.norm_g + DM, scr, r, lane, false); continue; } r -= I3;
;         p0_transpose_item(p.w4, DM, DM, W4T, nullptr, scr, r, lane, false);
.LBB0_14:
	v_cmp_lt_i32_e32 vcc, s18, v10
	s_and_saveexec_b64 s[8:9], vcc
	s_xor_b64 s[8:9], exec, s[8:9]
	s_cbranch_execz .LBB0_24
	v_cmp_lt_u32_e32 vcc, s19, v10
	s_and_saveexec_b64 s[10:11], vcc
	s_xor_b64 s[10:11], exec, s[10:11]
	s_cbranch_execz .LBB0_21
	v_cmp_lt_u32_e32 vcc, s24, v10
	s_and_saveexec_b64 s[12:13], vcc
	s_xor_b64 s[12:13], exec, s[12:13]
	s_cbranch_execz .LBB0_18
	v_add_u32_e32 v2, 0xa000, v10
	v_and_b32_e32 v54, 0xffc0, v2
	v_and_b32_e32 v55, 0x7e0, v29
	v_or_b32_e32 v38, v54, v1
	v_lshlrev_b32_e32 v2, 2, v55
	v_lshl_add_u64 v[22:23], v[14:15], 0, v[2:3]
	v_lshlrev_b32_e32 v2, 13, v38
	v_lshl_add_u64 v[22:23], v[22:23], 0, v[2:3]
	v_add_co_u32_e32 v38, vcc, 0x4000, v22
	s_nop 1
	v_addc_co_u32_e32 v39, vcc, 0, v23, vcc
	v_add_co_u32_e32 v40, vcc, 0x8000, v22
	s_nop 1
	v_addc_co_u32_e32 v41, vcc, 0, v23, vcc
	v_add_co_u32_e32 v42, vcc, 0xc000, v22
	s_nop 1
	v_addc_co_u32_e32 v43, vcc, 0, v23, vcc
	v_add_co_u32_e32 v44, vcc, 0x10000, v22
	s_nop 1
	v_addc_co_u32_e32 v45, vcc, 0, v23, vcc
	v_add_co_u32_e32 v46, vcc, 0x14000, v22
	s_nop 1
	v_addc_co_u32_e32 v47, vcc, 0, v23, vcc
	v_add_co_u32_e32 v48, vcc, 0x18000, v22
	s_nop 1
	v_addc_co_u32_e32 v49, vcc, 0, v23, vcc
	v_add_co_u32_e32 v50, vcc, 0x1c000, v22
	s_nop 1
	v_addc_co_u32_e32 v51, vcc, 0, v23, vcc
	global_load_dword v2, v[22:23], off nt
	global_load_dword v56, v[38:39], off nt
	global_load_dword v57, v[40:41], off nt
	global_load_dword v58, v[42:43], off nt
	global_load_dword v59, v[44:45], off nt
	global_load_dword v60, v[46:47], off nt
	global_load_dword v61, v[48:49], off nt
	global_load_dword v62, v[50:51], off nt
	v_add_co_u32_e32 v38, vcc, 0x20000, v22
	s_nop 1
	v_addc_co_u32_e32 v39, vcc, 0, v23, vcc
	v_add_co_u32_e32 v40, vcc, 0x24000, v22
	s_nop 1
	v_addc_co_u32_e32 v41, vcc, 0, v23, vcc
	v_add_co_u32_e32 v42, vcc, 0x28000, v22
	s_nop 1
	v_addc_co_u32_e32 v43, vcc, 0, v23, vcc
	v_add_co_u32_e32 v44, vcc, 0x2c000, v22
	s_nop 1
	v_addc_co_u32_e32 v45, vcc, 0, v23, vcc
	v_add_co_u32_e32 v46, vcc, 0x30000, v22
	s_nop 1
	v_addc_co_u32_e32 v47, vcc, 0, v23, vcc
	v_add_co_u32_e32 v48, vcc, 0x34000, v22
	s_nop 1
	v_addc_co_u32_e32 v49, vcc, 0, v23, vcc
	v_add_co_u32_e32 v50, vcc, 0x38000, v22
	s_nop 1
	v_addc_co_u32_e32 v51, vcc, 0, v23, vcc
	v_add_co_u32_e32 v52, vcc, 0x3c000, v22
	s_nop 1
	v_addc_co_u32_e32 v53, vcc, 0, v23, vcc
	global_load_dword v63, v[38:39], off nt
	global_load_dword v64, v[40:41], off nt
	global_load_dword v65, v[42:43], off nt
	global_load_dword v66, v[44:45], off nt
	global_load_dword v67, v[46:47], off nt
	global_load_dword v68, v[48:49], off nt
	global_load_dword v69, v[50:51], off nt
	global_load_dword v70, v[52:53], off nt
	v_add_co_u32_e32 v38, vcc, 0x40000, v22
	s_nop 1
	v_addc_co_u32_e32 v39, vcc, 0, v23, vcc
	v_add_co_u32_e32 v40, vcc, 0x44000, v22
	s_nop 1
	v_addc_co_u32_e32 v41, vcc, 0, v23, vcc
	v_add_co_u32_e32 v42, vcc, 0x48000, v22
	s_nop 1
	v_addc_co_u32_e32 v43, vcc, 0, v23, vcc
	v_add_co_u32_e32 v44, vcc, 0x4c000, v22
	s_nop 1
	v_addc_co_u32_e32 v45, vcc, 0, v23, vcc
	v_add_co_u32_e32 v46, vcc, 0x50000, v22
	s_nop 1
	v_addc_co_u32_e32 v47, vcc, 0, v23, vcc
	v_add_co_u32_e32 v48, vcc, 0x54000, v22
	s_nop 1
	v_addc_co_u32_e32 v49, vcc, 0, v23, vcc
	v_add_co_u32_e32 v50, vcc, 0x58000, v22
	s_nop 1
	v_addc_co_u32_e32 v51, vcc, 0, v23, vcc
	v_add_co_u32_e32 v52, vcc, 0x5c000, v22
	s_nop 1
	v_addc_co_u32_e32 v53, vcc, 0, v23, vcc
	global_load_dword v71, v[38:39], off nt
	global_load_dword v72, v[40:41], off nt
	global_load_dword v73, v[42:43], off nt
	global_load_dword v74, v[44:45], off nt
	global_load_dword v75, v[46:47], off nt
	global_load_dword v76, v[48:49], off nt
	global_load_dword v77, v[50:51], off nt
	s_nop 0
	global_load_dword v52, v[52:53], off nt
	v_add_co_u32_e32 v38, vcc, 0x60000, v22
	s_nop 1
	v_addc_co_u32_e32 v39, vcc, 0, v23, vcc
	v_add_co_u32_e32 v40, vcc, 0x64000, v22
	s_nop 1
	v_addc_co_u32_e32 v41, vcc, 0, v23, vcc
	v_add_co_u32_e32 v42, vcc, 0x68000, v22
	s_nop 1
	v_addc_co_u32_e32 v43, vcc, 0, v23, vcc
	v_add_co_u32_e32 v44, vcc, 0x6c000, v22
	s_nop 1
	v_addc_co_u32_e32 v45, vcc, 0, v23, vcc
	v_add_co_u32_e32 v46, vcc, 0x70000, v22
	s_nop 1
	v_addc_co_u32_e32 v47, vcc, 0, v23, vcc
	v_add_co_u32_e32 v48, vcc, 0x74000, v22
	s_nop 1
	v_addc_co_u32_e32 v49, vcc, 0, v23, vcc
	v_add_co_u32_e32 v50, vcc, 0x78000, v22
	s_nop 1
	v_addc_co_u32_e32 v51, vcc, 0, v23, vcc
	v_add_co_u32_e32 v22, vcc, 0x7c000, v22
	s_nop 1
	v_addc_co_u32_e32 v23, vcc, 0, v23, vcc
	global_load_dword v38, v[38:39], off nt
	s_nop 0
	global_load_dword v39, v[40:41], off nt
	s_nop 0
	global_load_dword v40, v[42:43], off nt
	global_load_dword v41, v[44:45], off nt
	s_nop 0
	global_load_dword v42, v[46:47], off nt
	global_load_dword v43, v[48:49], off nt
	global_load_dword v44, v[50:51], off nt
	s_nop 0
	global_load_dword v22, v[22:23], off nt
	s_waitcnt vmcnt(30)
	ds_write2_b32 v11, v2, v56 offset1:66
	s_waitcnt vmcnt(28)
	ds_write2_b32 v11, v57, v58 offset0:132 offset1:198
	s_waitcnt vmcnt(26)
	ds_write2_b32 v31, v59, v60 offset0:8 offset1:74
	s_waitcnt vmcnt(24)
	ds_write2_b32 v31, v61, v62 offset0:140 offset1:206
	s_waitcnt vmcnt(22)
	ds_write2_b32 v32, v63, v64 offset0:16 offset1:82
	s_waitcnt vmcnt(20)
	ds_write2_b32 v32, v65, v66 offset0:148 offset1:214
	s_waitcnt vmcnt(18)
	ds_write2_b32 v33, v67, v68 offset0:24 offset1:90
	s_waitcnt vmcnt(16)
	ds_write2_b32 v33, v69, v70 offset0:156 offset1:222
	s_waitcnt vmcnt(14)
	ds_write2_b32 v34, v71, v72 offset0:32 offset1:98
	s_waitcnt vmcnt(12)
	ds_write2_b32 v34, v73, v74 offset0:164 offset1:230
	s_waitcnt vmcnt(10)
	ds_write2_b32 v35, v75, v76 offset0:40 offset1:106
	s_waitcnt vmcnt(8)
; #define LAS __attribute__((address_space(3)))
; __device__ __forceinline__ unsigned cvt_pk_bf16(float lo, float hi) { unsigned r; asm volatile("v_cvt_pk_bf16_f32 %0, %1, %2" : "=v"(r) : "v"(lo), "v"(hi)); return r; }
; __device__ __forceinline__ void p0_transpose_item(const float* W, int K, int N, bf16_t* WT, const float* gk, LAS float* scr, int item, int lane, bool w1map) {
;     ...
;     for (int i = 0; i < 32; ++i) wv[i] = __builtin_nontemporal_load(W + (size_t)(k0 + 2 * i + (lane >> 5)) * N + n0 + (lane & 31));
;     if (gk) {
; #pragma unroll
;         for (int i = 0; i < 32; ++i) wv[i] *= gk[k0 + 2 * i + (lane >> 5)];
;     }
; #pragma unroll
;     for (int i = 0; i < 32; ++i) scr[(2 * i + (lane >> 5)) * 33 + (lane & 31)] = wv[i];
;     asm volatile("s_waitcnt lgkmcnt(0)" ::: "memory");
;     const int c = lane & 7;
; #pragma unroll
;     for (int j = 0; j < 4; ++j) { const int n = (lane >> 3) + 8 * j; const LAS float* s = scr + (8 * c) * 33 + n;
;         u32x4 o; o.x = cvt_pk_bf16(s[0 * 33], s[1 * 33]); o.y = cvt_pk_bf16(s[2 * 33], s[3 * 33]); o.z = cvt_pk_bf16(s[4 * 33], s[5 * 33]); o.w = cvt_pk_bf16(s[6 * 33], s[7 * 33]);
;         *(u32x4*)(WT + (size_t)(nd0 + n) * K + k0 + 8 * c) = o; }
	ds_write2_b32 v35, v77, v52 offset0:172 offset1:238
	s_waitcnt vmcnt(6)
	ds_write2_b32 v36, v38, v39 offset0:48 offset1:114
	s_waitcnt vmcnt(4)
	ds_write2_b32 v36, v40, v41 offset0:180 offset1:246
	s_waitcnt vmcnt(2)
	ds_write2_b32 v37, v42, v43 offset0:56 offset1:122
	s_waitcnt vmcnt(0)
	ds_write2_b32 v37, v44, v22 offset0:188 offset1:254
	s_waitcnt lgkmcnt(0)
	ds_read2_b32 v[22:23], v25 offset1:33
	s_waitcnt lgkmcnt(0)
	v_cvt_pk_bf16_f32 v38, v22, v23
	ds_read2_b32 v[22:23], v25 offset0:66 offset1:99
	v_lshlrev_b32_e32 v2, 1, v54
	s_waitcnt lgkmcnt(0)
	v_cvt_pk_bf16_f32 v39, v22, v23
	ds_read2_b32 v[22:23], v25 offset0:132 offset1:165
	v_lshl_add_u64 v[42:43], v[4:5], 0, v[2:3]
	v_or_b32_e32 v2, v55, v24
	s_waitcnt lgkmcnt(0)
	v_cvt_pk_bf16_f32 v40, v22, v23
	ds_read2_b32 v[22:23], v25 offset0:198 offset1:231
	v_lshlrev_b32_e32 v2, 12, v2
	s_waitcnt lgkmcnt(0)
	v_cvt_pk_bf16_f32 v41, v22, v23
	ds_read2_b32 v[22:23], v25 offset0:8 offset1:41
	v_lshl_add_u64 v[44:45], v[42:43], 0, v[2:3]
	global_store_dwordx4 v[44:45], v[38:41], off sc1
	v_or_b32_e32 v2, v55, v26
	v_lshlrev_b32_e32 v2, 12, v2
	s_waitcnt lgkmcnt(0)
	v_cvt_pk_bf16_f32 v38, v22, v23
	ds_read2_b32 v[22:23], v25 offset0:74 offset1:107
	s_waitcnt lgkmcnt(0)
	v_cvt_pk_bf16_f32 v39, v22, v23
	ds_read2_b32 v[22:23], v25 offset0:140 offset1:173
	s_waitcnt lgkmcnt(0)
	v_cvt_pk_bf16_f32 v40, v22, v23
	ds_read2_b32 v[22:23], v25 offset0:206 offset1:239
	s_waitcnt lgkmcnt(0)
	v_cvt_pk_bf16_f32 v41, v22, v23
	ds_read2_b32 v[22:23], v25 offset0:16 offset1:49
	v_lshl_add_u64 v[44:45], v[42:43], 0, v[2:3]
	global_store_dwordx4 v[44:45], v[38:41], off sc1
	v_or_b32_e32 v2, v55, v27
	v_lshlrev_b32_e32 v2, 12, v2
	s_waitcnt lgkmcnt(0)
	v_cvt_pk_bf16_f32 v38, v22, v23
	ds_read2_b32 v[22:23], v25 offset0:82 offset1:115
	s_waitcnt lgkmcnt(0)
	v_cvt_pk_bf16_f32 v39, v22, v23
	ds_read2_b32 v[22:23], v25 offset0:148 offset1:181
	s_waitcnt lgkmcnt(0)
	v_cvt_pk_bf16_f32 v40, v22, v23
	ds_read2_b32 v[22:23], v25 offset0:214 offset1:247
	s_waitcnt lgkmcnt(0)
	v_cvt_pk_bf16_f32 v41, v22, v23
	ds_read2_b32 v[22:23], v25 offset0:24 offset1:57
	v_lshl_add_u64 v[44:45], v[42:43], 0, v[2:3]
	global_store_dwordx4 v[44:45], v[38:41], off sc1
	v_or_b32_e32 v2, v55, v28
	v_lshlrev_b32_e32 v2, 12, v2
	s_waitcnt lgkmcnt(0)
	v_cvt_pk_bf16_f32 v38, v22, v23
	ds_read2_b32 v[22:23], v25 offset0:90 offset1:123
	s_waitcnt lgkmcnt(0)
	v_cvt_pk_bf16_f32 v39, v22, v23
	ds_read2_b32 v[22:23], v25 offset0:156 offset1:189
	s_waitcnt lgkmcnt(0)
	v_cvt_pk_bf16_f32 v40, v22, v23
	ds_read2_b32 v[22:23], v25 offset0:222 offset1:255
	s_waitcnt lgkmcnt(0)
	v_cvt_pk_bf16_f32 v41, v22, v23
	v_lshl_add_u64 v[22:23], v[42:43], 0, v[2:3]
	global_store_dwordx4 v[22:23], v[38:41], off sc1
	s_waitcnt lgkmcnt(0)
.LBB0_18:
	s_andn2_saveexec_b64 s[12:13], s[12:13]
	s_cbranch_execz .LBB0_20
	v_add_u32_e32 v2, 0xc000, v10
	v_bfe_u32 v23, v2, 8, 8
	v_and_b32_e32 v22, 0x1fe0, v29
	v_lshl_or_b32 v56, v23, 6, v1
	v_lshlrev_b32_e32 v2, 2, v22
	v_lshl_add_u64 v[38:39], v[16:17], 0, v[2:3]
	v_lshlrev_b32_e32 v2, 15, v56
	v_or_b32_e32 v57, 2, v56
	v_lshl_add_u64 v[40:41], v[38:39], 0, v[2:3]
	v_lshlrev_b32_e32 v2, 15, v57
	v_or_b32_e32 v58, 4, v56
	v_lshl_add_u64 v[42:43], v[38:39], 0, v[2:3]
	v_lshlrev_b32_e32 v2, 15, v58
	v_or_b32_e32 v59, 6, v56
	v_lshl_add_u64 v[44:45], v[38:39], 0, v[2:3]
	v_lshlrev_b32_e32 v2, 15, v59
	v_or_b32_e32 v60, 8, v56
	v_lshl_add_u64 v[46:47], v[38:39], 0, v[2:3]
	v_lshlrev_b32_e32 v2, 15, v60
	v_or_b32_e32 v61, 10, v56
	v_lshl_add_u64 v[48:49], v[38:39], 0, v[2:3]
	v_lshlrev_b32_e32 v2, 15, v61
	v_or_b32_e32 v62, 12, v56
	v_lshl_add_u64 v[50:51], v[38:39], 0, v[2:3]
	v_lshlrev_b32_e32 v2, 15, v62
	v_or_b32_e32 v63, 14, v56
	v_lshl_add_u64 v[52:53], v[38:39], 0, v[2:3]
	v_lshlrev_b32_e32 v2, 15, v63
	v_or_b32_e32 v72, 16, v56
	v_lshl_add_u64 v[54:55], v[38:39], 0, v[2:3]
	v_lshlrev_b32_e32 v2, 15, v72
	v_or_b32_e32 v73, 18, v56
	global_load_dword v64, v[40:41], off nt
	global_load_dword v65, v[42:43], off nt
	global_load_dword v66, v[44:45], off nt
	global_load_dword v67, v[46:47], off nt
	global_load_dword v68, v[48:49], off nt
	global_load_dword v69, v[50:51], off nt
	global_load_dword v70, v[52:53], off nt
	global_load_dword v71, v[54:55], off nt
	v_lshl_add_u64 v[40:41], v[38:39], 0, v[2:3]
	v_lshlrev_b32_e32 v2, 15, v73
	v_or_b32_e32 v74, 20, v56
	v_lshl_add_u64 v[42:43], v[38:39], 0, v[2:3]
	v_lshlrev_b32_e32 v2, 15, v74
	v_or_b32_e32 v75, 22, v56
	v_lshl_add_u64 v[44:45], v[38:39], 0, v[2:3]
	v_lshlrev_b32_e32 v2, 15, v75
	v_or_b32_e32 v76, 24, v56
	v_lshl_add_u64 v[46:47], v[38:39], 0, v[2:3]
	v_lshlrev_b32_e32 v2, 15, v76
	v_or_b32_e32 v77, 26, v56
	v_lshl_add_u64 v[48:49], v[38:39], 0, v[2:3]
	v_lshlrev_b32_e32 v2, 15, v77
	v_or_b32_e32 v78, 28, v56
	v_lshl_add_u64 v[50:51], v[38:39], 0, v[2:3]
	v_lshlrev_b32_e32 v2, 15, v78
	v_or_b32_e32 v79, 30, v56
	v_lshl_add_u64 v[52:53], v[38:39], 0, v[2:3]
	v_lshlrev_b32_e32 v2, 15, v79
	v_or_b32_e32 v88, 32, v56
	v_lshl_add_u64 v[54:55], v[38:39], 0, v[2:3]
	v_lshlrev_b32_e32 v2, 15, v88
	v_or_b32_e32 v89, 34, v56
	global_load_dword v80, v[40:41], off nt
	global_load_dword v81, v[42:43], off nt
	global_load_dword v82, v[44:45], off nt
	global_load_dword v83, v[46:47], off nt
	global_load_dword v84, v[48:49], off nt
	global_load_dword v85, v[50:51], off nt
	global_load_dword v86, v[52:53], off nt
	global_load_dword v87, v[54:55], off nt
	v_lshl_add_u64 v[40:41], v[38:39], 0, v[2:3]
	v_lshlrev_b32_e32 v2, 15, v89
	v_or_b32_e32 v90, 36, v56
	v_lshl_add_u64 v[42:43], v[38:39], 0, v[2:3]
	v_lshlrev_b32_e32 v2, 15, v90
	v_or_b32_e32 v91, 38, v56
	v_lshl_add_u64 v[44:45], v[38:39], 0, v[2:3]
; __device__ __forceinline__ void p0_transpose_item(const float* W, int K, int N, bf16_t* WT, const float* gk, LAS float* scr, int item, int lane, bool w1map) {
;     ...
;     for (int i = 0; i < 32; ++i) wv[i] = __builtin_nontemporal_load(W + (size_t)(k0 + 2 * i + (lane >> 5)) * N + n0 + (lane & 31));
;     if (gk) {
; #pragma unroll
;         for (int i = 0; i < 32; ++i) wv[i] *= gk[k0 + 2 * i + (lane >> 5)];
	v_lshlrev_b32_e32 v2, 15, v91
	v_or_b32_e32 v92, 40, v56
	v_lshl_add_u64 v[46:47], v[38:39], 0, v[2:3]
	v_lshlrev_b32_e32 v2, 15, v92
	v_or_b32_e32 v93, 42, v56
	v_lshl_add_u64 v[48:49], v[38:39], 0, v[2:3]
	v_lshlrev_b32_e32 v2, 15, v93
	v_or_b32_e32 v94, 44, v56
	v_lshl_add_u64 v[50:51], v[38:39], 0, v[2:3]
	v_lshlrev_b32_e32 v2, 15, v94
	v_or_b32_e32 v95, 46, v56
	v_lshl_add_u64 v[52:53], v[38:39], 0, v[2:3]
	v_lshlrev_b32_e32 v2, 15, v95
	v_lshl_add_u64 v[54:55], v[38:39], 0, v[2:3]
	global_load_dword v96, v[40:41], off nt
	global_load_dword v97, v[42:43], off nt
	global_load_dword v98, v[44:45], off nt
	global_load_dword v99, v[46:47], off nt
	global_load_dword v100, v[48:49], off nt
	global_load_dword v101, v[50:51], off nt
	global_load_dword v102, v[52:53], off nt
	s_nop 0
	global_load_dword v54, v[54:55], off nt
	v_or_b32_e32 v55, 48, v56
	v_lshlrev_b32_e32 v2, 15, v55
	v_or_b32_e32 v103, 50, v56
	v_lshl_add_u64 v[40:41], v[38:39], 0, v[2:3]
	v_lshlrev_b32_e32 v2, 15, v103
	v_or_b32_e32 v104, 52, v56
	v_lshl_add_u64 v[42:43], v[38:39], 0, v[2:3]
	v_lshlrev_b32_e32 v2, 15, v104
	v_or_b32_e32 v105, 54, v56
	v_lshl_add_u64 v[44:45], v[38:39], 0, v[2:3]
	v_lshlrev_b32_e32 v2, 15, v105
	v_or_b32_e32 v106, 56, v56
	v_lshl_add_u64 v[46:47], v[38:39], 0, v[2:3]
	v_lshlrev_b32_e32 v2, 15, v106
	v_or_b32_e32 v107, 58, v56
	v_lshl_add_u64 v[48:49], v[38:39], 0, v[2:3]
	v_lshlrev_b32_e32 v2, 15, v107
	v_or_b32_e32 v108, 60, v56
	v_lshl_add_u64 v[50:51], v[38:39], 0, v[2:3]
	v_lshlrev_b32_e32 v2, 15, v108
	v_or_b32_e32 v109, 62, v56
	v_lshl_add_u64 v[52:53], v[38:39], 0, v[2:3]
	v_lshlrev_b32_e32 v2, 15, v109
	v_lshl_add_u64 v[38:39], v[38:39], 0, v[2:3]
	global_load_dword v2, v[40:41], off nt
	s_nop 0
	global_load_dword v40, v[42:43], off nt
	global_load_dword v41, v[44:45], off nt
	s_nop 0
	global_load_dword v42, v[46:47], off nt
	global_load_dword v43, v[48:49], off nt
	global_load_dword v44, v[50:51], off nt
	global_load_dword v45, v[52:53], off nt
	s_nop 0
	global_load_dword v38, v[38:39], off nt
	v_lshlrev_b32_e32 v39, 2, v56
	v_lshlrev_b32_e32 v46, 2, v57
	v_lshlrev_b32_e32 v47, 2, v58
	v_lshlrev_b32_e32 v48, 2, v59
	v_lshlrev_b32_e32 v49, 2, v60
	v_lshlrev_b32_e32 v50, 2, v61
	v_lshlrev_b32_e32 v51, 2, v62
	v_lshlrev_b32_e32 v52, 2, v63
	v_lshlrev_b32_e32 v53, 2, v72
	v_lshlrev_b32_e32 v56, 2, v73
	v_lshlrev_b32_e32 v57, 2, v74
	v_lshlrev_b32_e32 v58, 2, v75
	v_lshlrev_b32_e32 v59, 2, v76
	v_lshlrev_b32_e32 v60, 2, v77
	v_lshlrev_b32_e32 v61, 2, v78
	v_lshlrev_b32_e32 v62, 2, v79
	v_lshlrev_b32_e32 v63, 2, v88
	v_lshlrev_b32_e32 v72, 2, v89
	v_lshlrev_b32_e32 v73, 2, v90
	v_lshlrev_b32_e32 v74, 2, v91
	v_lshlrev_b32_e32 v75, 2, v92
	v_lshlrev_b32_e32 v76, 2, v93
	v_lshlrev_b32_e32 v77, 2, v94
	v_lshlrev_b32_e32 v78, 2, v95
	v_lshlrev_b32_e32 v55, 2, v55
	v_lshlrev_b32_e32 v79, 2, v103
	v_lshlrev_b32_e32 v88, 2, v104
	v_lshlrev_b32_e32 v89, 2, v105
	v_lshlrev_b32_e32 v90, 2, v106
	v_lshlrev_b32_e32 v91, 2, v107
	v_lshlrev_b32_e32 v92, 2, v108
	v_lshlrev_b32_e32 v93, 2, v109
	global_load_dword v39, v39, s[4:5]
	s_nop 0
	global_load_dword v46, v46, s[4:5]
	s_nop 0
	global_load_dword v47, v47, s[4:5]
	s_nop 0
	global_load_dword v48, v48, s[4:5]
	s_nop 0
	global_load_dword v49, v49, s[4:5]
	s_nop 0
	global_load_dword v50, v50, s[4:5]
	s_nop 0
	global_load_dword v51, v51, s[4:5]
	s_nop 0
	global_load_dword v52, v52, s[4:5]
	s_nop 0
	global_load_dword v53, v53, s[4:5]
	s_nop 0
	global_load_dword v56, v56, s[4:5]
	s_nop 0
	global_load_dword v57, v57, s[4:5]
	s_nop 0
	global_load_dword v58, v58, s[4:5]
	s_nop 0
	global_load_dword v59, v59, s[4:5]
	s_nop 0
	global_load_dword v60, v60, s[4:5]
	s_nop 0
	global_load_dword v61, v61, s[4:5]
	s_nop 0
	global_load_dword v62, v62, s[4:5]
	s_nop 0
	global_load_dword v63, v63, s[4:5]
	s_nop 0
	global_load_dword v72, v72, s[4:5]
	s_nop 0
	global_load_dword v73, v73, s[4:5]
	s_nop 0
	global_load_dword v74, v74, s[4:5]
	s_nop 0
	global_load_dword v75, v75, s[4:5]
	s_nop 0
	global_load_dword v76, v76, s[4:5]
	s_nop 0
	global_load_dword v77, v77, s[4:5]
	s_nop 0
	global_load_dword v78, v78, s[4:5]
	s_nop 0
	global_load_dword v55, v55, s[4:5]
	s_nop 0
	global_load_dword v79, v79, s[4:5]
	s_nop 0
	global_load_dword v88, v88, s[4:5]
	s_nop 0
	global_load_dword v89, v89, s[4:5]
	s_nop 0
	global_load_dword v90, v90, s[4:5]
	s_nop 0
	global_load_dword v91, v91, s[4:5]
	s_nop 0
	global_load_dword v92, v92, s[4:5]
	s_nop 0
	global_load_dword v93, v93, s[4:5]
	s_waitcnt vmcnt(31)
	v_mul_f32_e32 v39, v64, v39
	s_waitcnt vmcnt(30)
	v_mul_f32_e32 v46, v65, v46
	s_waitcnt vmcnt(29)
	v_mul_f32_e32 v47, v66, v47
	s_waitcnt vmcnt(28)
; #define LAS __attribute__((address_space(3)))
; __device__ __forceinline__ unsigned cvt_pk_bf16(float lo, float hi) { unsigned r; asm volatile("v_cvt_pk_bf16_f32 %0, %1, %2" : "=v"(r) : "v"(lo), "v"(hi)); return r; }
; __device__ __forceinline__ void p0_transpose_item(const float* W, int K, int N, bf16_t* WT, const float* gk, LAS float* scr, int item, int lane, bool w1map) {
;     ...
;         for (int i = 0; i < 32; ++i) wv[i] *= gk[k0 + 2 * i + (lane >> 5)];
;     }
; #pragma unroll
;     for (int i = 0; i < 32; ++i) scr[(2 * i + (lane >> 5)) * 33 + (lane & 31)] = wv[i];
;     asm volatile("s_waitcnt lgkmcnt(0)" ::: "memory");
;     const int c = lane & 7;
; #pragma unroll
;     for (int j = 0; j < 4; ++j) { const int n = (lane >> 3) + 8 * j; const LAS float* s = scr + (8 * c) * 33 + n;
;         u32x4 o; o.x = cvt_pk_bf16(s[0 * 33], s[1 * 33]); o.y = cvt_pk_bf16(s[2 * 33], s[3 * 33]); o.z = cvt_pk_bf16(s[4 * 33], s[5 * 33]); o.w = cvt_pk_bf16(s[6 * 33], s[7 * 33]);
;         *(u32x4*)(WT + (size_t)(nd0 + n) * K + k0 + 8 * c) = o; }
	v_mul_f32_e32 v48, v67, v48
	s_waitcnt vmcnt(27)
	v_mul_f32_e32 v49, v68, v49
	s_waitcnt vmcnt(26)
	v_mul_f32_e32 v50, v69, v50
	s_waitcnt vmcnt(25)
	v_mul_f32_e32 v51, v70, v51
	s_waitcnt vmcnt(24)
	v_mul_f32_e32 v52, v71, v52
	s_waitcnt vmcnt(23)
	v_mul_f32_e32 v53, v80, v53
	s_waitcnt vmcnt(22)
	v_mul_f32_e32 v56, v81, v56
	s_waitcnt vmcnt(21)
	v_mul_f32_e32 v57, v82, v57
	s_waitcnt vmcnt(20)
	v_mul_f32_e32 v58, v83, v58
	s_waitcnt vmcnt(19)
	v_mul_f32_e32 v59, v84, v59
	s_waitcnt vmcnt(18)
	v_mul_f32_e32 v60, v85, v60
	s_waitcnt vmcnt(17)
	v_mul_f32_e32 v61, v86, v61
	s_waitcnt vmcnt(16)
	v_mul_f32_e32 v62, v87, v62
	s_waitcnt vmcnt(15)
	v_mul_f32_e32 v63, v96, v63
	s_waitcnt vmcnt(14)
	v_mul_f32_e32 v64, v97, v72
	s_waitcnt vmcnt(13)
	v_mul_f32_e32 v65, v98, v73
	s_waitcnt vmcnt(12)
	v_mul_f32_e32 v66, v99, v74
	s_waitcnt vmcnt(11)
	v_mul_f32_e32 v67, v100, v75
	s_waitcnt vmcnt(10)
	v_mul_f32_e32 v68, v101, v76
	s_waitcnt vmcnt(9)
	v_mul_f32_e32 v69, v102, v77
	s_waitcnt vmcnt(8)
	v_mul_f32_e32 v54, v54, v78
	s_waitcnt vmcnt(7)
	v_mul_f32_e32 v2, v2, v55
	s_waitcnt vmcnt(6)
	v_mul_f32_e32 v40, v40, v79
	s_waitcnt vmcnt(5)
	v_mul_f32_e32 v41, v41, v88
	s_waitcnt vmcnt(4)
	v_mul_f32_e32 v42, v42, v89
	s_waitcnt vmcnt(3)
	v_mul_f32_e32 v43, v43, v90
	s_waitcnt vmcnt(2)
	v_mul_f32_e32 v44, v44, v91
	s_waitcnt vmcnt(1)
	v_mul_f32_e32 v45, v45, v92
	s_waitcnt vmcnt(0)
	v_mul_f32_e32 v38, v38, v93
	ds_write2_b32 v11, v39, v46 offset1:66
	ds_write2_b32 v11, v47, v48 offset0:132 offset1:198
	ds_write2_b32 v31, v49, v50 offset0:8 offset1:74
	ds_write2_b32 v31, v51, v52 offset0:140 offset1:206
	ds_write2_b32 v32, v53, v56 offset0:16 offset1:82
	ds_write2_b32 v32, v57, v58 offset0:148 offset1:214
	ds_write2_b32 v33, v59, v60 offset0:24 offset1:90
	ds_write2_b32 v33, v61, v62 offset0:156 offset1:222
	ds_write2_b32 v34, v63, v64 offset0:32 offset1:98
	ds_write2_b32 v34, v65, v66 offset0:164 offset1:230
	ds_write2_b32 v35, v67, v68 offset0:40 offset1:106
	ds_write2_b32 v35, v69, v54 offset0:172 offset1:238
	ds_write2_b32 v36, v2, v40 offset0:48 offset1:114
	ds_write2_b32 v36, v41, v42 offset0:180 offset1:246
	ds_write2_b32 v37, v43, v44 offset0:56 offset1:122
	ds_write2_b32 v37, v45, v38 offset0:188 offset1:254
	s_waitcnt lgkmcnt(0)
	ds_read2_b32 v[38:39], v25 offset1:33
	v_lshlrev_b32_e32 v2, 7, v23
	s_waitcnt lgkmcnt(0)
	v_cvt_pk_bf16_f32 v38, v38, v39
	ds_read2_b32 v[40:41], v25 offset0:66 offset1:99
	v_lshl_add_u64 v[44:45], v[6:7], 0, v[2:3]
	v_or_b32_e32 v2, v22, v24
	s_waitcnt lgkmcnt(0)
	v_cvt_pk_bf16_f32 v39, v40, v41
	ds_read2_b32 v[40:41], v25 offset0:132 offset1:165
	v_lshlrev_b32_e32 v2, 12, v2
	s_waitcnt lgkmcnt(0)
	v_cvt_pk_bf16_f32 v40, v40, v41
	ds_read2_b32 v[42:43], v25 offset0:198 offset1:231
	s_waitcnt lgkmcnt(0)
	v_cvt_pk_bf16_f32 v41, v42, v43
	v_lshl_add_u64 v[46:47], v[44:45], 0, v[2:3]
	ds_read2_b32 v[42:43], v25 offset0:8 offset1:41
	global_store_dwordx4 v[46:47], v[38:41], off sc1
	v_or_b32_e32 v2, v22, v26
	v_lshlrev_b32_e32 v2, 12, v2
	s_waitcnt lgkmcnt(0)
	v_cvt_pk_bf16_f32 v38, v42, v43
	ds_read2_b32 v[40:41], v25 offset0:74 offset1:107
	s_waitcnt lgkmcnt(0)
	v_cvt_pk_bf16_f32 v39, v40, v41
	ds_read2_b32 v[40:41], v25 offset0:140 offset1:173
	s_waitcnt lgkmcnt(0)
	v_cvt_pk_bf16_f32 v40, v40, v41
	ds_read2_b32 v[42:43], v25 offset0:206 offset1:239
	s_waitcnt lgkmcnt(0)
	v_cvt_pk_bf16_f32 v41, v42, v43
	v_lshl_add_u64 v[46:47], v[44:45], 0, v[2:3]
	ds_read2_b32 v[42:43], v25 offset0:16 offset1:49
	global_store_dwordx4 v[46:47], v[38:41], off sc1
	v_or_b32_e32 v2, v22, v27
	v_lshlrev_b32_e32 v2, 12, v2
	s_waitcnt lgkmcnt(0)
	v_cvt_pk_bf16_f32 v38, v42, v43
	ds_read2_b32 v[40:41], v25 offset0:82 offset1:115
	s_waitcnt lgkmcnt(0)
	v_cvt_pk_bf16_f32 v39, v40, v41
	ds_read2_b32 v[40:41], v25 offset0:148 offset1:181
	s_waitcnt lgkmcnt(0)
	v_cvt_pk_bf16_f32 v40, v40, v41
	ds_read2_b32 v[42:43], v25 offset0:214 offset1:247
	s_waitcnt lgkmcnt(0)
	v_cvt_pk_bf16_f32 v41, v42, v43
	v_lshl_add_u64 v[46:47], v[44:45], 0, v[2:3]
	v_or_b32_e32 v2, v22, v28
	ds_read2_b32 v[42:43], v25 offset0:24 offset1:57
	global_store_dwordx4 v[46:47], v[38:41], off sc1
	v_lshlrev_b32_e32 v2, 12, v2
	v_lshl_add_u64 v[22:23], v[44:45], 0, v[2:3]
	s_waitcnt lgkmcnt(0)
	v_cvt_pk_bf16_f32 v38, v42, v43
	ds_read2_b32 v[40:41], v25 offset0:90 offset1:123
	s_waitcnt lgkmcnt(0)
	v_cvt_pk_bf16_f32 v39, v40, v41
	ds_read2_b32 v[40:41], v25 offset0:156 offset1:189
	s_waitcnt lgkmcnt(0)
	v_cvt_pk_bf16_f32 v40, v40, v41
	ds_read2_b32 v[42:43], v25 offset0:222 offset1:255
	s_waitcnt lgkmcnt(0)
	v_cvt_pk_bf16_f32 v41, v42, v43
	global_store_dwordx4 v[22:23], v[38:41], off sc1
	s_waitcnt lgkmcnt(0)

; __device__ __forceinline__ void p0_transpose_item(const float* W, int K, int N, bf16_t* WT, const float* gk, LAS float* scr, int item, int lane, bool w1map) {
;     const int nblk = N / 32, kb = item / nblk, nb = item % nblk, k0 = 64 * kb, n0 = 32 * nb;
;     int nd0 = n0;
;     if (w1map) { if (n0 < GW) nd0 = (n0 >> 7) * 256 + (n0 & 127); else if (n0 < 2 * GW) nd0 = 2 * GW + (n0 - GW); else { const int c = n0 - 2 * GW; nd0 = (c >> 7) * 256 + 128 + (c & 127); } }
;     float wv[32];
; #pragma unroll
;     for (int i = 0; i < 32; ++i) wv[i] = __builtin_nontemporal_load(W + (size_t)(k0 + 2 * i + (lane >> 5)) * N + n0 + (lane & 31));
.LBB0_21:
	s_andn2_saveexec_b64 s[10:11], s[10:11]
	s_cbranch_execz .LBB0_23
	v_add_u32_e32 v2, 0xd000, v10
	v_and_b32_e32 v54, 0xffc0, v2
	v_and_b32_e32 v55, 0x7e0, v29
	v_or_b32_e32 v38, v54, v1
	v_lshlrev_b32_e32 v2, 2, v55
	v_lshl_add_u64 v[22:23], v[18:19], 0, v[2:3]
	v_lshlrev_b32_e32 v2, 13, v38
	v_lshl_add_u64 v[22:23], v[22:23], 0, v[2:3]
	v_add_co_u32_e32 v38, vcc, 0x4000, v22
	s_nop 1
	v_addc_co_u32_e32 v39, vcc, 0, v23, vcc
	v_add_co_u32_e32 v40, vcc, 0x8000, v22
	s_nop 1
	v_addc_co_u32_e32 v41, vcc, 0, v23, vcc
	v_add_co_u32_e32 v42, vcc, 0xc000, v22
	s_nop 1
	v_addc_co_u32_e32 v43, vcc, 0, v23, vcc
	v_add_co_u32_e32 v44, vcc, 0x10000, v22
	s_nop 1
	v_addc_co_u32_e32 v45, vcc, 0, v23, vcc
	v_add_co_u32_e32 v46, vcc, 0x14000, v22
	s_nop 1
	v_addc_co_u32_e32 v47, vcc, 0, v23, vcc
	v_add_co_u32_e32 v48, vcc, 0x18000, v22
	s_nop 1
	v_addc_co_u32_e32 v49, vcc, 0, v23, vcc
	v_add_co_u32_e32 v50, vcc, 0x1c000, v22
	s_nop 1
	v_addc_co_u32_e32 v51, vcc, 0, v23, vcc
	global_load_dword v2, v[22:23], off nt
	global_load_dword v56, v[38:39], off nt
	global_load_dword v57, v[40:41], off nt
	global_load_dword v58, v[42:43], off nt
	global_load_dword v59, v[44:45], off nt
	global_load_dword v60, v[46:47], off nt
	global_load_dword v61, v[48:49], off nt
	global_load_dword v62, v[50:51], off nt
	v_add_co_u32_e32 v38, vcc, 0x20000, v22
	s_nop 1
	v_addc_co_u32_e32 v39, vcc, 0, v23, vcc
	v_add_co_u32_e32 v40, vcc, 0x24000, v22
	s_nop 1
	v_addc_co_u32_e32 v41, vcc, 0, v23, vcc
	v_add_co_u32_e32 v42, vcc, 0x28000, v22
	s_nop 1
	v_addc_co_u32_e32 v43, vcc, 0, v23, vcc
	v_add_co_u32_e32 v44, vcc, 0x2c000, v22
	s_nop 1
	v_addc_co_u32_e32 v45, vcc, 0, v23, vcc
	v_add_co_u32_e32 v46, vcc, 0x30000, v22
	s_nop 1
	v_addc_co_u32_e32 v47, vcc, 0, v23, vcc
	v_add_co_u32_e32 v48, vcc, 0x34000, v22
	s_nop 1
	v_addc_co_u32_e32 v49, vcc, 0, v23, vcc
	v_add_co_u32_e32 v50, vcc, 0x38000, v22
	s_nop 1
	v_addc_co_u32_e32 v51, vcc, 0, v23, vcc
	v_add_co_u32_e32 v52, vcc, 0x3c000, v22
	s_nop 1
	v_addc_co_u32_e32 v53, vcc, 0, v23, vcc
	global_load_dword v63, v[38:39], off nt
	global_load_dword v64, v[40:41], off nt
	global_load_dword v65, v[42:43], off nt
	global_load_dword v66, v[44:45], off nt
	global_load_dword v67, v[46:47], off nt
	global_load_dword v68, v[48:49], off nt
	global_load_dword v69, v[50:51], off nt
	global_load_dword v70, v[52:53], off nt
	v_add_co_u32_e32 v38, vcc, 0x40000, v22
	s_nop 1
	v_addc_co_u32_e32 v39, vcc, 0, v23, vcc
	v_add_co_u32_e32 v40, vcc, 0x44000, v22
	s_nop 1
	v_addc_co_u32_e32 v41, vcc, 0, v23, vcc
	v_add_co_u32_e32 v42, vcc, 0x48000, v22
	s_nop 1
	v_addc_co_u32_e32 v43, vcc, 0, v23, vcc
	v_add_co_u32_e32 v44, vcc, 0x4c000, v22
	s_nop 1
	v_addc_co_u32_e32 v45, vcc, 0, v23, vcc
	v_add_co_u32_e32 v46, vcc, 0x50000, v22
	s_nop 1
	v_addc_co_u32_e32 v47, vcc, 0, v23, vcc
	v_add_co_u32_e32 v48, vcc, 0x54000, v22
	s_nop 1
	v_addc_co_u32_e32 v49, vcc, 0, v23, vcc
	v_add_co_u32_e32 v50, vcc, 0x58000, v22
	s_nop 1
	v_addc_co_u32_e32 v51, vcc, 0, v23, vcc
	v_add_co_u32_e32 v52, vcc, 0x5c000, v22
	s_nop 1
	v_addc_co_u32_e32 v53, vcc, 0, v23, vcc
	global_load_dword v71, v[38:39], off nt
	global_load_dword v72, v[40:41], off nt
	global_load_dword v73, v[42:43], off nt
	global_load_dword v74, v[44:45], off nt
	global_load_dword v75, v[46:47], off nt
	global_load_dword v76, v[48:49], off nt
	global_load_dword v77, v[50:51], off nt
	s_nop 0
	global_load_dword v52, v[52:53], off nt
	v_add_co_u32_e32 v38, vcc, 0x60000, v22
	s_nop 1
	v_addc_co_u32_e32 v39, vcc, 0, v23, vcc
	v_add_co_u32_e32 v40, vcc, 0x64000, v22
	s_nop 1
	v_addc_co_u32_e32 v41, vcc, 0, v23, vcc
	v_add_co_u32_e32 v42, vcc, 0x68000, v22
	s_nop 1
	v_addc_co_u32_e32 v43, vcc, 0, v23, vcc
	v_add_co_u32_e32 v44, vcc, 0x6c000, v22
	s_nop 1
	v_addc_co_u32_e32 v45, vcc, 0, v23, vcc
	v_add_co_u32_e32 v46, vcc, 0x70000, v22
	s_nop 1
	v_addc_co_u32_e32 v47, vcc, 0, v23, vcc
	v_add_co_u32_e32 v48, vcc, 0x74000, v22
	s_nop 1
	v_addc_co_u32_e32 v49, vcc, 0, v23, vcc
	v_add_co_u32_e32 v50, vcc, 0x78000, v22
	s_nop 1
	v_addc_co_u32_e32 v51, vcc, 0, v23, vcc
	v_add_co_u32_e32 v22, vcc, 0x7c000, v22
	s_nop 1
	v_addc_co_u32_e32 v23, vcc, 0, v23, vcc
	global_load_dword v38, v[38:39], off nt
	s_nop 0
	global_load_dword v39, v[40:41], off nt
	s_nop 0
	global_load_dword v40, v[42:43], off nt
	global_load_dword v41, v[44:45], off nt
	s_nop 0
	global_load_dword v42, v[46:47], off nt
	global_load_dword v43, v[48:49], off nt
	global_load_dword v44, v[50:51], off nt
	s_nop 0
	global_load_dword v22, v[22:23], off nt
	s_waitcnt vmcnt(30)
; #define LAS __attribute__((address_space(3)))
; __device__ __forceinline__ unsigned cvt_pk_bf16(float lo, float hi) { unsigned r; asm volatile("v_cvt_pk_bf16_f32 %0, %1, %2" : "=v"(r) : "v"(lo), "v"(hi)); return r; }
; __device__ __forceinline__ void p0_transpose_item(const float* W, int K, int N, bf16_t* WT, const float* gk, LAS float* scr, int item, int lane, bool w1map) {
;     ...
;     for (int i = 0; i < 32; ++i) scr[(2 * i + (lane >> 5)) * 33 + (lane & 31)] = wv[i];
;     asm volatile("s_waitcnt lgkmcnt(0)" ::: "memory");
;     const int c = lane & 7;
; #pragma unroll
;     for (int j = 0; j < 4; ++j) { const int n = (lane >> 3) + 8 * j; const LAS float* s = scr + (8 * c) * 33 + n;
;         u32x4 o; o.x = cvt_pk_bf16(s[0 * 33], s[1 * 33]); o.y = cvt_pk_bf16(s[2 * 33], s[3 * 33]); o.z = cvt_pk_bf16(s[4 * 33], s[5 * 33]); o.w = cvt_pk_bf16(s[6 * 33], s[7 * 33]);
;         *(u32x4*)(WT + (size_t)(nd0 + n) * K + k0 + 8 * c) = o; }
	ds_write2_b32 v11, v2, v56 offset1:66
	s_waitcnt vmcnt(28)
	ds_write2_b32 v11, v57, v58 offset0:132 offset1:198
	s_waitcnt vmcnt(26)
	ds_write2_b32 v31, v59, v60 offset0:8 offset1:74
	s_waitcnt vmcnt(24)
	ds_write2_b32 v31, v61, v62 offset0:140 offset1:206
	s_waitcnt vmcnt(22)
	ds_write2_b32 v32, v63, v64 offset0:16 offset1:82
	s_waitcnt vmcnt(20)
	ds_write2_b32 v32, v65, v66 offset0:148 offset1:214
	s_waitcnt vmcnt(18)
	ds_write2_b32 v33, v67, v68 offset0:24 offset1:90
	s_waitcnt vmcnt(16)
	ds_write2_b32 v33, v69, v70 offset0:156 offset1:222
	s_waitcnt vmcnt(14)
	ds_write2_b32 v34, v71, v72 offset0:32 offset1:98
	s_waitcnt vmcnt(12)
	ds_write2_b32 v34, v73, v74 offset0:164 offset1:230
	s_waitcnt vmcnt(10)
	ds_write2_b32 v35, v75, v76 offset0:40 offset1:106
	s_waitcnt vmcnt(8)
	ds_write2_b32 v35, v77, v52 offset0:172 offset1:238
	s_waitcnt vmcnt(6)
	ds_write2_b32 v36, v38, v39 offset0:48 offset1:114
	s_waitcnt vmcnt(4)
	ds_write2_b32 v36, v40, v41 offset0:180 offset1:246
	s_waitcnt vmcnt(2)
	ds_write2_b32 v37, v42, v43 offset0:56 offset1:122
	s_waitcnt vmcnt(0)
	ds_write2_b32 v37, v44, v22 offset0:188 offset1:254
	s_waitcnt lgkmcnt(0)
	ds_read2_b32 v[22:23], v25 offset1:33
	s_waitcnt lgkmcnt(0)
	v_cvt_pk_bf16_f32 v38, v22, v23
	ds_read2_b32 v[22:23], v25 offset0:66 offset1:99
	v_lshlrev_b32_e32 v2, 1, v54
	s_waitcnt lgkmcnt(0)
	v_cvt_pk_bf16_f32 v39, v22, v23
	ds_read2_b32 v[22:23], v25 offset0:132 offset1:165
	v_lshl_add_u64 v[42:43], v[8:9], 0, v[2:3]
	v_or_b32_e32 v2, v55, v24
	s_waitcnt lgkmcnt(0)
	v_cvt_pk_bf16_f32 v40, v22, v23
	ds_read2_b32 v[22:23], v25 offset0:198 offset1:231
	v_lshlrev_b32_e32 v2, 13, v2
	s_waitcnt lgkmcnt(0)
	v_cvt_pk_bf16_f32 v41, v22, v23
	ds_read2_b32 v[22:23], v25 offset0:8 offset1:41
	v_lshl_add_u64 v[44:45], v[42:43], 0, v[2:3]
	global_store_dwordx4 v[44:45], v[38:41], off sc1
	v_or_b32_e32 v2, v55, v26
	v_lshlrev_b32_e32 v2, 13, v2
	s_waitcnt lgkmcnt(0)
	v_cvt_pk_bf16_f32 v38, v22, v23
	ds_read2_b32 v[22:23], v25 offset0:74 offset1:107
	s_waitcnt lgkmcnt(0)
	v_cvt_pk_bf16_f32 v39, v22, v23
	ds_read2_b32 v[22:23], v25 offset0:140 offset1:173
	s_waitcnt lgkmcnt(0)
	v_cvt_pk_bf16_f32 v40, v22, v23
	ds_read2_b32 v[22:23], v25 offset0:206 offset1:239
	s_waitcnt lgkmcnt(0)
	v_cvt_pk_bf16_f32 v41, v22, v23
	ds_read2_b32 v[22:23], v25 offset0:16 offset1:49
	v_lshl_add_u64 v[44:45], v[42:43], 0, v[2:3]
	global_store_dwordx4 v[44:45], v[38:41], off sc1
	v_or_b32_e32 v2, v55, v27
	v_lshlrev_b32_e32 v2, 13, v2
	s_waitcnt lgkmcnt(0)
	v_cvt_pk_bf16_f32 v38, v22, v23
	ds_read2_b32 v[22:23], v25 offset0:82 offset1:115
	s_waitcnt lgkmcnt(0)
	v_cvt_pk_bf16_f32 v39, v22, v23
	ds_read2_b32 v[22:23], v25 offset0:148 offset1:181
	s_waitcnt lgkmcnt(0)
	v_cvt_pk_bf16_f32 v40, v22, v23
	ds_read2_b32 v[22:23], v25 offset0:214 offset1:247
	s_waitcnt lgkmcnt(0)
	v_cvt_pk_bf16_f32 v41, v22, v23
	ds_read2_b32 v[22:23], v25 offset0:24 offset1:57
	v_lshl_add_u64 v[44:45], v[42:43], 0, v[2:3]
	global_store_dwordx4 v[44:45], v[38:41], off sc1
	v_or_b32_e32 v2, v55, v28
	v_lshlrev_b32_e32 v2, 13, v2
	s_waitcnt lgkmcnt(0)
	v_cvt_pk_bf16_f32 v38, v22, v23
	ds_read2_b32 v[22:23], v25 offset0:90 offset1:123
	s_waitcnt lgkmcnt(0)
	v_cvt_pk_bf16_f32 v39, v22, v23
	ds_read2_b32 v[22:23], v25 offset0:156 offset1:189
	s_waitcnt lgkmcnt(0)
	v_cvt_pk_bf16_f32 v40, v22, v23
	ds_read2_b32 v[22:23], v25 offset0:222 offset1:255
	s_waitcnt lgkmcnt(0)
	v_cvt_pk_bf16_f32 v41, v22, v23
	v_lshl_add_u64 v[22:23], v[42:43], 0, v[2:3]
	global_store_dwordx4 v[22:23], v[38:41], off sc1
	s_waitcnt lgkmcnt(0)
